# attention heads: lazy-rescale bookkeeping (new max, alpha exp, lsum*alpha, selects) moved onto the rare need-rescale branch; common path only tests the threshold
# speedup vs baseline: 1.0022x; 1.0022x over previous
.Lattn1_nomask:
	s_add_i32 s9, s78, 0x10000
	s_and_b32 s33, s9, 0x18000
	s_and_b32 s76, s78, 0x18000
	v_add_u32_e32 v250, s33, v237
	v_add_u32_e32 v250, v250, v228
	ds_read_b128 v[128:131], v250 offset:16384
	ds_read_b128 v[132:135], v250 offset:20480
	ds_read_b128 v[136:139], v250 offset:24576
	ds_read_b128 v[140:143], v250 offset:28672
	v_add_u32_e32 v251, s76, v235
	v_add_u32_e32 v250, v251, v228
	ds_read_b128 v[144:147], v250
	ds_read_b128 v[148:151], v250 offset:4096
	v_add_u32_e32 v250, v251, v231
	ds_read_b128 v[152:155], v250
	ds_read_b128 v[156:159], v250 offset:4096
	s_add_i32 s0, s74, s38
	s_addk_i32 s0, 0xc0
	s_mul_i32 s0, s0, s14
	s_lshl_b32 s92, s46, 1
	s_add_i32 s0, s0, s92
	s_addk_i32 s0, 0x1c00
	s_add_u32 s98, s82, s0
	s_addc_u32 s99, s83, 0
	s_add_i32 s0, s78, 0x8000
	s_and_b32 s0, s0, 0x18000
	s_add_i32 s0, s5, s0
	s_mov_b32 m0, s0
	s_nop 0
	global_load_lds_dwordx4 v244, s[98:99]
	s_add_i32 m0, s0, 0x2000
	s_add_u32 s98, s98, 0x80
	s_addc_u32 s99, s99, 0
	global_load_lds_dwordx4 v244, s[98:99]
	s_lshl_b32 s1, s17, 13
	s_add_u32 s98, s40, s1
	s_addc_u32 s99, s41, 0
	s_add_i32 m0, s0, 0x4000
	s_nop 0
	global_load_lds_dwordx4 v245, s[98:99]
	s_add_i32 m0, s0, 0x6000
	s_add_u32 s98, s98, 0x80000
	s_addc_u32 s99, s99, 0
	global_load_lds_dwordx4 v245, s[98:99]
	v_max3_f32 v246, v64, v65, v66
	v_max3_f32 v247, v72, v73, v74
	v_max3_f32 v248, v80, v81, v82
	v_max3_f32 v249, v88, v89, v90
	v_max3_f32 v246, v246, v67, v68
	v_max3_f32 v247, v247, v75, v76
	v_max3_f32 v248, v248, v83, v84
	v_max3_f32 v249, v249, v91, v92
	s_waitcnt lgkmcnt(7)
	v_mfma_f32_32x32x16_bf16 v[0:15], v[128:131], v[96:99], v[0:15]
	v_max3_f32 v246, v246, v69, v70
	v_max3_f32 v247, v247, v77, v78
	v_max3_f32 v248, v248, v85, v86
	v_max3_f32 v249, v249, v93, v94
	v_max3_f32 v246, v246, v71, v247
	v_max3_f32 v247, v248, v87, v249
	s_waitcnt lgkmcnt(6)
	v_mfma_f32_32x32x16_bf16 v[48:63], v[132:135], v[96:99], v[48:63]
	v_max3_f32 v246, v246, v79, v95
	s_nop 0
	v_max3_f32 v246, v246, v247, v247
	s_nop 0
	v_mov_b32_e32 v247, v246
	s_nop 1
	v_permlane32_swap_b32_e32 v246, v247
	v_max3_f32 v246, v246, v247, v247
	s_nop 0
	s_waitcnt lgkmcnt(5)
	v_mfma_f32_32x32x16_bf16 v[32:47], v[136:139], v[96:99], v[32:47]
	v_add_f32_e32 v247, 0x41000000, v212
	v_cmp_gt_f32_e32 vcc, v246, v247
	s_cmp_eq_u64 vcc, 0
	s_cbranch_scc0 .Lneed_A1
	v_mov_b32_e32 v194, v100
.Lneed_A1_join:
	s_waitcnt lgkmcnt(4)
	v_mfma_f32_32x32x16_bf16 v[16:31], v[140:143], v[96:99], v[16:31]
	v_sub_f32_e32 v140, v92, v212
	v_sub_f32_e32 v141, v93, v212
	v_sub_f32_e32 v138, v90, v212
	v_sub_f32_e32 v139, v91, v212
	s_waitcnt lgkmcnt(3)
	v_mfma_f32_32x32x16_bf16 v[96:111], v[144:147], v[160:163], 0
	v_sub_f32_e32 v142, v94, v212
	v_sub_f32_e32 v143, v95, v212
	v_sub_f32_e32 v92, v80, v212
	v_sub_f32_e32 v93, v81, v212
	v_sub_f32_e32 v128, v82, v212
	v_sub_f32_e32 v129, v83, v212
	s_waitcnt lgkmcnt(2)
	v_mfma_f32_32x32x16_bf16 v[112:127], v[148:151], v[160:163], 0
	v_sub_f32_e32 v130, v68, v212
	v_sub_f32_e32 v131, v69, v212
	v_sub_f32_e32 v90, v64, v212
	v_sub_f32_e32 v91, v65, v212
	v_sub_f32_e32 v132, v84, v212
	v_sub_f32_e32 v133, v85, v212
	s_waitcnt lgkmcnt(1)
	v_mfma_f32_32x32x16_bf16 v[96:111], v[152:155], v[164:167], v[96:111]
	v_sub_f32_e32 v94, v66, v212
	v_sub_f32_e32 v95, v67, v212
	v_sub_f32_e32 v134, v86, v212
	v_sub_f32_e32 v135, v87, v212
	v_sub_f32_e32 v136, v88, v212
	v_sub_f32_e32 v137, v89, v212
	s_waitcnt lgkmcnt(0)
	v_mfma_f32_32x32x16_bf16 v[112:127], v[156:159], v[164:167], v[112:127]
	v_sub_f32_e32 v144, v70, v212
	v_sub_f32_e32 v145, v71, v212
	v_sub_f32_e32 v148, v74, v212
	v_sub_f32_e32 v149, v75, v212
	v_sub_f32_e32 v150, v76, v212
	v_sub_f32_e32 v151, v77, v212
	v_sub_f32_e32 v146, v72, v212
	v_sub_f32_e32 v147, v73, v212
	v_sub_f32_e32 v152, v78, v212
	v_sub_f32_e32 v153, v79, v212
	v_mov_b32_e32 v68, v250
	s_branch .Lattn_body_1
.Lneed_A1:
	v_max_f32_e32 v251, v212, v246
	v_sub_f32_e32 v247, v212, v251
	v_exp_f32_e32 v250, v247
	v_mov_b32_e32 v212, v251
	v_mul_f32_e32 v194, v100, v250
	s_branch .Lneed_A1_join

.LBB0_840:
	s_add_i32 s0, s78, 0xffff8000
	s_and_b32 s10, s0, 0x18000
	v_add_u32_e32 v76, s10, v237
	v_add_u32_e32 v76, v76, v228
	ds_read_b128 v[80:83], v76 offset:16384
	ds_read_b128 v[84:87], v76 offset:20480
	ds_read_b128 v[88:91], v76 offset:24576
	ds_read_b128 v[92:95], v76 offset:28672
	v_max3_f32 v68, v96, v97, v98
	v_max3_f32 v70, v104, v105, v106
	v_max3_f32 v71, v112, v113, v114
	v_max3_f32 v72, v120, v121, v122
	v_max3_f32 v68, v68, v99, v100
	v_max3_f32 v70, v70, v107, v108
	v_max3_f32 v71, v71, v115, v116
	v_max3_f32 v72, v72, v123, v124
	s_waitcnt lgkmcnt(3)
	v_mfma_f32_32x32x16_bf16 v[0:15], v[80:83], v[64:67], v[0:15]
	v_max3_f32 v68, v68, v101, v102
	v_max3_f32 v70, v70, v109, v110
	v_max3_f32 v71, v71, v117, v118
	v_max3_f32 v72, v72, v125, v126
	s_xor_b32 s33, s10, 0x10000
	v_max3_f32 v68, v68, v103, v70
	v_max3_f32 v70, v71, v119, v72
	s_waitcnt lgkmcnt(2)
	v_mfma_f32_32x32x16_bf16 v[48:63], v[84:87], v[64:67], v[48:63]
	v_max3_f32 v68, v68, v111, v127
	s_nop 0
	v_max3_f32 v68, v68, v70, v70
	s_nop 0
	v_mov_b32_e32 v70, v68
	s_nop 1
	v_permlane32_swap_b32_e32 v68, v70
	v_max3_f32 v68, v68, v70, v70
	s_nop 0
	s_waitcnt lgkmcnt(1)
	v_mfma_f32_32x32x16_bf16 v[32:47], v[88:91], v[64:67], v[32:47]
	v_add_f32_e32 v70, 0x41000000, v212
	v_cmp_gt_f32_e32 vcc, v68, v70
	s_cmp_eq_u64 vcc, 0
	s_cbranch_scc0 .Lneed_B1
	v_mov_b32_e32 v194, v69
.Lneed_B1_join:
	s_waitcnt lgkmcnt(0)
	v_mfma_f32_32x32x16_bf16 v[16:31], v[92:95], v[64:67], v[16:31]
	v_add_u32_e32 v182, s10, v237
	v_add_u32_e32 v158, s33, v235
	v_add_u32_e32 v88, v158, v231
	v_add_u32_e32 v150, v182, v231
	v_add_u32_e32 v159, v158, v230
	v_add_u32_e32 v141, v182, v230
	v_sub_f32_e32 v180, v102, v212
	v_sub_f32_e32 v181, v103, v212
	v_sub_f32_e32 v116, v116, v212
	v_sub_f32_e32 v117, v117, v212
	v_sub_f32_e32 v108, v108, v212
	v_sub_f32_e32 v109, v109, v212
	v_sub_f32_e32 v124, v124, v212
	v_sub_f32_e32 v125, v125, v212
	v_exp_f32_e32 v116, v116
	v_exp_f32_e32 v117, v117
	v_exp_f32_e32 v108, v108
	v_exp_f32_e32 v124, v124
	v_exp_f32_e32 v109, v109
	v_add_u32_e32 v68, v158, v228
	v_add_u32_e32 v158, v158, v229
	v_exp_f32_e32 v125, v125
	v_sub_f32_e32 v114, v114, v212
	v_sub_f32_e32 v115, v115, v212
	v_sub_f32_e32 v118, v118, v212
	v_sub_f32_e32 v119, v119, v212
	v_sub_f32_e32 v122, v122, v212
	v_sub_f32_e32 v123, v123, v212
	v_sub_f32_e32 v110, v110, v212
	v_sub_f32_e32 v111, v111, v212
	ds_read_b128 v[64:67], v68
	ds_read_b128 v[80:83], v68 offset:4096
	ds_read_b128 v[84:87], v88
	ds_read_b128 v[142:145], v88 offset:4096
	v_sub_f32_e32 v126, v126, v212
	v_sub_f32_e32 v127, v127, v212
	v_sub_f32_e32 v106, v106, v212
	v_sub_f32_e32 v107, v107, v212
	v_exp_f32_e32 v114, v114
	v_exp_f32_e32 v115, v115
	v_exp_f32_e32 v118, v118
	s_waitcnt lgkmcnt(0)
	v_mfma_f32_32x32x16_bf16 v[64:79], v[64:67], v[160:163], 0
	v_exp_f32_e32 v119, v119
	v_exp_f32_e32 v122, v122
	v_exp_f32_e32 v123, v123
	v_exp_f32_e32 v110, v110
	v_exp_f32_e32 v126, v126
	v_exp_f32_e32 v111, v111
	v_exp_f32_e32 v127, v127
	v_mfma_f32_32x32x16_bf16 v[64:79], v[84:87], v[164:167], v[64:79]
	v_sub_f32_e32 v104, v104, v212
	v_sub_f32_e32 v105, v105, v212
	v_sub_f32_e32 v112, v112, v212
	v_sub_f32_e32 v113, v113, v212
	v_sub_f32_e32 v120, v120, v212
	v_sub_f32_e32 v121, v121, v212
	v_cvt_pk_bf16_f32 v183, v118, v119
	v_exp_f32_e32 v112, v112
	v_exp_f32_e32 v113, v113
	v_exp_f32_e32 v120, v120
	v_mfma_f32_32x32x16_bf16 v[80:95], v[80:83], v[160:163], 0
	v_exp_f32_e32 v121, v121
	v_cvt_pk_bf16_f32 v186, v108, v109
	v_cvt_pk_bf16_f32 v187, v110, v111
	v_mfma_f32_32x32x16_bf16 v[80:95], v[142:145], v[164:167], v[80:95]
	ds_read_b128 v[142:145], v150 offset:16384
	ds_read_b128 v[146:149], v150 offset:20480
	s_waitcnt lgkmcnt(0)
	v_mfma_f32_32x32x16_bf16 v[0:15], v[142:145], v[136:139], v[0:15]
	ds_read_b128 v[142:145], v150 offset:24576
	ds_read_b128 v[150:153], v150 offset:28672
	ds_read_b128 v[154:157], v159
	ds_read_b128 v[176:179], v159 offset:4096
	v_mfma_f32_32x32x16_bf16 v[48:63], v[146:149], v[136:139], v[48:63]
	ds_read_b128 v[146:149], v158
	ds_read_b128 v[238:241], v158 offset:4096
	v_sub_f32_e32 v158, v96, v212
	v_sub_f32_e32 v159, v97, v212
	s_waitcnt lgkmcnt(0)
	v_mfma_f32_32x32x16_bf16 v[32:47], v[142:145], v[136:139], v[32:47]
	v_sub_f32_e32 v142, v98, v212
	v_sub_f32_e32 v143, v99, v212
	v_sub_f32_e32 v144, v100, v212
	v_sub_f32_e32 v145, v101, v212
	ds_read_b128 v[96:99], v141 offset:16384
	ds_read_b128 v[100:103], v141 offset:20480
	s_waitcnt lgkmcnt(0)
	v_mfma_f32_32x32x16_bf16 v[0:15], v[96:99], v[132:135], v[0:15]
	ds_read_b128 v[96:99], v141 offset:24576
	v_mfma_f32_32x32x16_bf16 v[48:63], v[100:103], v[132:135], v[48:63]
	ds_read_b128 v[100:103], v141 offset:28672
	v_add_u32_e32 v141, v182, v229
	v_cvt_pk_bf16_f32 v182, v116, v117
	v_mfma_f32_32x32x16_bf16 v[16:31], v[150:153], v[136:139], v[16:31]
	v_exp_f32_e32 v138, v142
	v_exp_f32_e32 v139, v143
	v_exp_f32_e32 v142, v144
	v_exp_f32_e32 v143, v145
	v_exp_f32_e32 v144, v180
	v_exp_f32_e32 v145, v181
	v_exp_f32_e32 v136, v158
	s_waitcnt lgkmcnt(0)
	v_mfma_f32_32x32x16_bf16 v[32:47], v[96:99], v[132:135], v[32:47]
	ds_read_b128 v[96:99], v141 offset:16384
	v_exp_f32_e32 v137, v159
	v_cvt_pk_bf16_f32 v180, v112, v113
	v_cvt_pk_bf16_f32 v181, v114, v115
	v_add_f32_e32 v152, v136, v112
	v_add_f32_e32 v153, v137, v113
	v_mfma_f32_32x32x16_bf16 v[16:31], v[100:103], v[132:135], v[16:31]
	v_add_f32_e64 v100, v108, v124
	v_add_f32_e64 v101, v109, v125
	v_add_f32_e64 v102, v142, v116
	v_add_f32_e64 v103, v143, v117
	v_exp_f32_e32 v134, v106
	v_exp_f32_e32 v135, v107
	v_exp_f32_e32 v132, v104
	v_exp_f32_e32 v133, v105
	v_add_f32_e32 v106, v138, v114
	v_add_f32_e32 v107, v139, v115
	v_mfma_f32_32x32x16_bf16 v[64:79], v[154:157], v[168:171], v[64:79]
	v_add_f32_e64 v154, v102, v100
	v_add_f32_e64 v155, v103, v101
	ds_read_b128 v[100:103], v141 offset:20480
	v_add_f32_e64 v104, v134, v122
	v_add_f32_e64 v105, v135, v123
	v_add_f32_e32 v150, v132, v120
	v_add_f32_e32 v151, v133, v121
	v_add_f32_e32 v104, v106, v104
	v_add_f32_e32 v105, v107, v105
	v_cvt_pk_bf16_f32 v184, v132, v133
	v_cvt_pk_bf16_f32 v185, v134, v135
	v_mfma_f32_32x32x16_bf16 v[64:79], v[146:149], v[172:175], v[64:79]
	v_add_f32_e64 v146, v110, v126
	v_add_f32_e64 v147, v111, v127
	v_add_f32_e64 v148, v144, v118
	v_add_f32_e64 v149, v145, v119
	s_waitcnt lgkmcnt(0)
	v_mfma_f32_32x32x16_bf16 v[0:15], v[96:99], v[128:131], v[0:15]
	v_add_f32_e64 v98, v148, v146
	v_add_f32_e64 v99, v149, v147
	v_add_f32_e64 v96, v152, v150
	v_add_f32_e64 v97, v153, v151
	v_add_f32_e64 v98, v104, v98
	v_add_f32_e64 v99, v105, v99
	ds_read_b128 v[104:107], v141 offset:24576
	v_add_f32_e32 v96, v96, v154
	v_add_f32_e32 v97, v97, v155
	s_nop 0
	v_add_f32_e32 v96, v96, v97
	v_mfma_f32_32x32x16_bf16 v[48:63], v[100:103], v[128:131], v[48:63]
	ds_read_b128 v[100:103], v141 offset:28672
	v_add_f32_e32 v97, v98, v99
	v_add_f32_e32 v146, v96, v97
	v_cvt_pk_bf16_f32 v96, v136, v137
	v_cvt_pk_bf16_f32 v97, v138, v139
	v_cvt_pk_bf16_f32 v98, v142, v143
	v_cvt_pk_bf16_f32 v99, v144, v145
	v_mfma_f32_32x32x16_bf16 v[80:95], v[176:179], v[168:171], v[80:95]
	v_cvt_pk_bf16_f32 v176, v120, v121
	v_cvt_pk_bf16_f32 v177, v122, v123
	v_cvt_pk_bf16_f32 v178, v124, v125
	v_cvt_pk_bf16_f32 v179, v126, v127
	s_waitcnt lgkmcnt(0)
	v_mfma_f32_32x32x16_bf16 v[32:47], v[104:107], v[128:131], v[32:47]
	v_mfma_f32_32x32x16_bf16 v[16:31], v[100:103], v[128:131], v[16:31]
	v_add_f32_e32 v100, v194, v146
	v_mfma_f32_32x32x16_bf16 v[80:95], v[238:241], v[172:175], v[80:95]
	s_cbranch_vccz .LBB0_842
	v_pk_mul_f32 v[14:15], v[140:141], v[14:15] op_sel_hi:[0,1]
	v_pk_mul_f32 v[12:13], v[140:141], v[12:13] op_sel_hi:[0,1]
	v_pk_mul_f32 v[10:11], v[140:141], v[10:11] op_sel_hi:[0,1]
	v_pk_mul_f32 v[8:9], v[140:141], v[8:9] op_sel_hi:[0,1]
	v_pk_mul_f32 v[6:7], v[140:141], v[6:7] op_sel_hi:[0,1]
	v_pk_mul_f32 v[4:5], v[140:141], v[4:5] op_sel_hi:[0,1]
	v_pk_mul_f32 v[2:3], v[140:141], v[2:3] op_sel_hi:[0,1]
	v_pk_mul_f32 v[0:1], v[140:141], v[0:1] op_sel_hi:[0,1]
	v_pk_mul_f32 v[62:63], v[140:141], v[62:63] op_sel_hi:[0,1]
	v_pk_mul_f32 v[60:61], v[140:141], v[60:61] op_sel_hi:[0,1]
	v_pk_mul_f32 v[58:59], v[140:141], v[58:59] op_sel_hi:[0,1]
	v_pk_mul_f32 v[56:57], v[140:141], v[56:57] op_sel_hi:[0,1]
	v_pk_mul_f32 v[54:55], v[140:141], v[54:55] op_sel_hi:[0,1]
	v_pk_mul_f32 v[52:53], v[140:141], v[52:53] op_sel_hi:[0,1]
	v_pk_mul_f32 v[50:51], v[140:141], v[50:51] op_sel_hi:[0,1]
	v_pk_mul_f32 v[48:49], v[140:141], v[48:49] op_sel_hi:[0,1]
	v_pk_mul_f32 v[46:47], v[140:141], v[46:47] op_sel_hi:[0,1]
	v_pk_mul_f32 v[44:45], v[140:141], v[44:45] op_sel_hi:[0,1]
	v_pk_mul_f32 v[42:43], v[140:141], v[42:43] op_sel_hi:[0,1]
	v_pk_mul_f32 v[40:41], v[140:141], v[40:41] op_sel_hi:[0,1]
	v_pk_mul_f32 v[38:39], v[140:141], v[38:39] op_sel_hi:[0,1]
	v_pk_mul_f32 v[36:37], v[140:141], v[36:37] op_sel_hi:[0,1]
	v_pk_mul_f32 v[34:35], v[140:141], v[34:35] op_sel_hi:[0,1]
	v_pk_mul_f32 v[32:33], v[140:141], v[32:33] op_sel_hi:[0,1]
	v_pk_mul_f32 v[30:31], v[140:141], v[30:31] op_sel_hi:[0,1]
	v_pk_mul_f32 v[28:29], v[140:141], v[28:29] op_sel_hi:[0,1]
	v_pk_mul_f32 v[26:27], v[140:141], v[26:27] op_sel_hi:[0,1]
	v_pk_mul_f32 v[24:25], v[140:141], v[24:25] op_sel_hi:[0,1]
	v_pk_mul_f32 v[22:23], v[140:141], v[22:23] op_sel_hi:[0,1]
	v_pk_mul_f32 v[20:21], v[140:141], v[20:21] op_sel_hi:[0,1]
	v_pk_mul_f32 v[18:19], v[140:141], v[18:19] op_sel_hi:[0,1]
	v_pk_mul_f32 v[16:17], v[140:141], v[16:17] op_sel_hi:[0,1]

.Lneed_B1:
	v_max_f32_e32 v141, v212, v68
	v_sub_f32_e32 v70, v212, v141
	v_exp_f32_e32 v140, v70
	v_mov_b32_e32 v212, v141
	v_mul_f32_e32 v194, v69, v140
	s_branch .Lneed_B1_join

.Lattn2_nomask:
	s_add_i32 s9, s34, 0x10000
	s_and_b32 s33, s9, 0x18000
	s_and_b32 s10, s34, 0x18000
	v_add_u32_e32 v250, s33, v237
	v_add_u32_e32 v250, v250, v230
	ds_read_b128 v[128:131], v250 offset:16384
	ds_read_b128 v[132:135], v250 offset:20480
	ds_read_b128 v[136:139], v250 offset:24576
	ds_read_b128 v[140:143], v250 offset:28672
	v_add_u32_e32 v251, s10, v236
	v_add_u32_e32 v250, v251, v230
	ds_read_b128 v[144:147], v250
	ds_read_b128 v[148:151], v250 offset:4096
	v_add_u32_e32 v250, v251, v233
	ds_read_b128 v[152:155], v250
	ds_read_b128 v[156:159], v250 offset:4096
	s_add_i32 s0, s74, s64
	s_addk_i32 s0, 0xc0
	s_mul_i32 s0, s0, s14
	s_add_i32 s0, s0, s92
	s_addk_i32 s0, 0x1c00
	s_add_u32 s98, s82, s0
	s_addc_u32 s99, s83, 0
	s_lshl_b32 s1, s17, 13
	s_add_u32 s46, s76, s1
	s_addc_u32 s47, s77, 0
	s_add_i32 s0, s34, 0x8000
	s_and_b32 s0, s0, 0x18000
	s_add_i32 s0, s5, s0
	s_mov_b32 m0, s0
	s_nop 0
	global_load_lds_dwordx4 v244, s[98:99]
	s_add_i32 m0, s0, 0x2000
	s_add_u32 s98, s98, 0x80
	s_addc_u32 s99, s99, 0
	global_load_lds_dwordx4 v244, s[98:99]
	s_add_i32 m0, s0, 0x4000
	s_nop 0
	global_load_lds_dwordx4 v245, s[46:47]
	s_add_i32 m0, s0, 0x6000
	s_add_u32 s46, s46, 0x80000
	s_addc_u32 s47, s47, 0
	global_load_lds_dwordx4 v245, s[46:47]
	v_max3_f32 v246, v64, v65, v66
	v_max3_f32 v247, v72, v73, v74
	v_max3_f32 v248, v80, v81, v82
	v_max3_f32 v249, v88, v89, v90
	v_max3_f32 v246, v246, v67, v68
	v_max3_f32 v247, v247, v75, v76
	v_max3_f32 v248, v248, v83, v84
	v_max3_f32 v249, v249, v91, v92
	s_waitcnt lgkmcnt(7)
	v_mfma_f32_32x32x16_bf16 v[0:15], v[128:131], v[96:99], v[0:15]
	v_max3_f32 v246, v246, v69, v70
	v_max3_f32 v247, v247, v77, v78
	v_max3_f32 v248, v248, v85, v86
	v_max3_f32 v249, v249, v93, v94
	v_max3_f32 v246, v246, v71, v247
	v_max3_f32 v247, v248, v87, v249
	s_waitcnt lgkmcnt(6)
	v_mfma_f32_32x32x16_bf16 v[48:63], v[132:135], v[96:99], v[48:63]
	v_max3_f32 v246, v246, v79, v95
	s_nop 0
	v_max3_f32 v246, v246, v247, v247
	s_nop 0
	v_mov_b32_e32 v247, v246
	s_nop 1
	v_permlane32_swap_b32_e32 v246, v247
	v_max3_f32 v246, v246, v247, v247
	s_nop 0
	s_waitcnt lgkmcnt(5)
	v_mfma_f32_32x32x16_bf16 v[32:47], v[136:139], v[96:99], v[32:47]
	v_add_f32_e32 v247, 0x41000000, v214
	v_cmp_gt_f32_e32 vcc, v246, v247
	s_cmp_eq_u64 vcc, 0
	s_cbranch_scc0 .Lneed_A2
	v_mov_b32_e32 v194, v100
.Lneed_A2_join:
	s_waitcnt lgkmcnt(4)
	v_mfma_f32_32x32x16_bf16 v[16:31], v[140:143], v[96:99], v[16:31]
	v_sub_f32_e32 v140, v92, v214
	v_sub_f32_e32 v141, v93, v214
	v_sub_f32_e32 v138, v90, v214
	v_sub_f32_e32 v139, v91, v214
	s_waitcnt lgkmcnt(3)
	v_mfma_f32_32x32x16_bf16 v[96:111], v[144:147], v[160:163], 0
	v_sub_f32_e32 v142, v94, v214
	v_sub_f32_e32 v143, v95, v214
	v_sub_f32_e32 v92, v80, v214
	v_sub_f32_e32 v93, v81, v214
	v_sub_f32_e32 v128, v82, v214
	v_sub_f32_e32 v129, v83, v214
	s_waitcnt lgkmcnt(2)
	v_mfma_f32_32x32x16_bf16 v[112:127], v[148:151], v[160:163], 0
	v_sub_f32_e32 v130, v68, v214
	v_sub_f32_e32 v131, v69, v214
	v_sub_f32_e32 v90, v64, v214
	v_sub_f32_e32 v91, v65, v214
	v_sub_f32_e32 v132, v84, v214
	v_sub_f32_e32 v133, v85, v214
	s_waitcnt lgkmcnt(1)
	v_mfma_f32_32x32x16_bf16 v[96:111], v[152:155], v[164:167], v[96:111]
	v_sub_f32_e32 v94, v66, v214
	v_sub_f32_e32 v95, v67, v214
	v_sub_f32_e32 v134, v86, v214
	v_sub_f32_e32 v135, v87, v214
	v_sub_f32_e32 v136, v88, v214
	v_sub_f32_e32 v137, v89, v214
	s_waitcnt lgkmcnt(0)
	v_mfma_f32_32x32x16_bf16 v[112:127], v[156:159], v[164:167], v[112:127]
	v_sub_f32_e32 v144, v70, v214
	v_sub_f32_e32 v145, v71, v214
	v_sub_f32_e32 v148, v74, v214
	v_sub_f32_e32 v149, v75, v214
	v_sub_f32_e32 v150, v76, v214
	v_sub_f32_e32 v151, v77, v214
	v_sub_f32_e32 v146, v72, v214
	v_sub_f32_e32 v147, v73, v214
	v_sub_f32_e32 v152, v78, v214
	v_sub_f32_e32 v153, v79, v214
	v_mov_b32_e32 v68, v250
	s_branch .Lattn_body_2
.Lneed_A2:
	v_max_f32_e32 v251, v214, v246
	v_sub_f32_e32 v247, v214, v251
	v_exp_f32_e32 v250, v247
	v_mov_b32_e32 v214, v251
	v_mul_f32_e32 v194, v100, v250
	s_branch .Lneed_A2_join

.LBB0_870:
	s_add_i32 s0, s34, 0xffff8000
	s_and_b32 s33, s0, 0x18000
	v_add_u32_e32 v76, s33, v237
	v_add_u32_e32 v76, v76, v230
	ds_read_b128 v[80:83], v76 offset:16384
	ds_read_b128 v[84:87], v76 offset:20480
	ds_read_b128 v[88:91], v76 offset:24576
	ds_read_b128 v[92:95], v76 offset:28672
	v_max3_f32 v68, v96, v97, v98
	v_max3_f32 v70, v104, v105, v106
	v_max3_f32 v71, v112, v113, v114
	v_max3_f32 v72, v120, v121, v122
	v_max3_f32 v68, v68, v99, v100
	v_max3_f32 v70, v70, v107, v108
	v_max3_f32 v71, v71, v115, v116
	v_max3_f32 v72, v72, v123, v124
	s_waitcnt lgkmcnt(3)
	v_mfma_f32_32x32x16_bf16 v[0:15], v[80:83], v[64:67], v[0:15]
	v_max3_f32 v68, v68, v101, v102
	v_max3_f32 v70, v70, v109, v110
	v_max3_f32 v71, v71, v117, v118
	v_max3_f32 v72, v72, v125, v126
	s_xor_b32 s34, s33, 0x10000
	v_max3_f32 v68, v68, v103, v70
	v_max3_f32 v70, v71, v119, v72
	s_waitcnt lgkmcnt(2)
	v_mfma_f32_32x32x16_bf16 v[48:63], v[84:87], v[64:67], v[48:63]
	v_max3_f32 v68, v68, v111, v127
	s_nop 0
	v_max3_f32 v68, v68, v70, v70
	s_nop 0
	v_mov_b32_e32 v70, v68
	s_nop 1
	v_permlane32_swap_b32_e32 v68, v70
	v_max3_f32 v68, v68, v70, v70
	s_nop 0
	s_waitcnt lgkmcnt(1)
	v_mfma_f32_32x32x16_bf16 v[32:47], v[88:91], v[64:67], v[32:47]
	v_add_f32_e32 v70, 0x41000000, v214
	v_cmp_gt_f32_e32 vcc, v68, v70
	s_cmp_eq_u64 vcc, 0
	s_cbranch_scc0 .Lneed_B2
	v_mov_b32_e32 v194, v69
.Lneed_B2_join:
	s_waitcnt lgkmcnt(0)
	v_mfma_f32_32x32x16_bf16 v[16:31], v[92:95], v[64:67], v[16:31]
	v_add_u32_e32 v182, s33, v237
	v_add_u32_e32 v158, s34, v236
	v_add_u32_e32 v88, v158, v233
	v_add_u32_e32 v150, v182, v233
	v_add_u32_e32 v159, v158, v232
	v_add_u32_e32 v141, v182, v232
	v_sub_f32_e32 v180, v102, v214
	v_sub_f32_e32 v181, v103, v214
	v_sub_f32_e32 v116, v116, v214
	v_sub_f32_e32 v117, v117, v214
	v_sub_f32_e32 v108, v108, v214
	v_sub_f32_e32 v109, v109, v214
	v_sub_f32_e32 v124, v124, v214
	v_sub_f32_e32 v125, v125, v214
	v_exp_f32_e32 v116, v116
	v_exp_f32_e32 v117, v117
	v_exp_f32_e32 v108, v108
	v_exp_f32_e32 v124, v124
	v_exp_f32_e32 v109, v109
	v_add_u32_e32 v68, v158, v230
	v_add_u32_e32 v158, v158, v231
	v_exp_f32_e32 v125, v125
	v_sub_f32_e32 v114, v114, v214
	v_sub_f32_e32 v115, v115, v214
	v_sub_f32_e32 v118, v118, v214
	v_sub_f32_e32 v119, v119, v214
	v_sub_f32_e32 v122, v122, v214
	v_sub_f32_e32 v123, v123, v214
	v_sub_f32_e32 v110, v110, v214
	v_sub_f32_e32 v111, v111, v214
	ds_read_b128 v[64:67], v68
	ds_read_b128 v[80:83], v68 offset:4096
	ds_read_b128 v[84:87], v88
	ds_read_b128 v[142:145], v88 offset:4096
	v_sub_f32_e32 v126, v126, v214
	v_sub_f32_e32 v127, v127, v214
	v_sub_f32_e32 v106, v106, v214
	v_sub_f32_e32 v107, v107, v214
	v_exp_f32_e32 v114, v114
	v_exp_f32_e32 v115, v115
	v_exp_f32_e32 v118, v118
	s_waitcnt lgkmcnt(0)
	v_mfma_f32_32x32x16_bf16 v[64:79], v[64:67], v[160:163], 0
	v_exp_f32_e32 v119, v119
	v_exp_f32_e32 v122, v122
	v_exp_f32_e32 v123, v123
	v_exp_f32_e32 v110, v110
	v_exp_f32_e32 v126, v126
	v_exp_f32_e32 v111, v111
	v_exp_f32_e32 v127, v127
	v_mfma_f32_32x32x16_bf16 v[64:79], v[84:87], v[164:167], v[64:79]
	v_sub_f32_e32 v104, v104, v214
	v_sub_f32_e32 v105, v105, v214
	v_sub_f32_e32 v112, v112, v214
	v_sub_f32_e32 v113, v113, v214
	v_sub_f32_e32 v120, v120, v214
	v_sub_f32_e32 v121, v121, v214
	v_cvt_pk_bf16_f32 v183, v118, v119
	v_exp_f32_e32 v112, v112
	v_exp_f32_e32 v113, v113
	v_exp_f32_e32 v120, v120
	v_mfma_f32_32x32x16_bf16 v[80:95], v[80:83], v[160:163], 0
	v_exp_f32_e32 v121, v121
	v_cvt_pk_bf16_f32 v186, v108, v109
	v_cvt_pk_bf16_f32 v187, v110, v111
	v_mfma_f32_32x32x16_bf16 v[80:95], v[142:145], v[164:167], v[80:95]
	ds_read_b128 v[142:145], v150 offset:16384
	ds_read_b128 v[146:149], v150 offset:20480
	s_waitcnt lgkmcnt(0)
	v_mfma_f32_32x32x16_bf16 v[0:15], v[142:145], v[136:139], v[0:15]
	ds_read_b128 v[142:145], v150 offset:24576
	ds_read_b128 v[150:153], v150 offset:28672
	ds_read_b128 v[154:157], v159
	ds_read_b128 v[176:179], v159 offset:4096
	v_mfma_f32_32x32x16_bf16 v[48:63], v[146:149], v[136:139], v[48:63]
	ds_read_b128 v[146:149], v158
	ds_read_b128 v[238:241], v158 offset:4096
	v_sub_f32_e32 v158, v96, v214
	v_sub_f32_e32 v159, v97, v214
	s_waitcnt lgkmcnt(0)
	v_mfma_f32_32x32x16_bf16 v[32:47], v[142:145], v[136:139], v[32:47]
	v_sub_f32_e32 v142, v98, v214
	v_sub_f32_e32 v143, v99, v214
	v_sub_f32_e32 v144, v100, v214
	v_sub_f32_e32 v145, v101, v214
	ds_read_b128 v[96:99], v141 offset:16384
	ds_read_b128 v[100:103], v141 offset:20480
	s_waitcnt lgkmcnt(0)
	v_mfma_f32_32x32x16_bf16 v[0:15], v[96:99], v[132:135], v[0:15]
	ds_read_b128 v[96:99], v141 offset:24576
	v_mfma_f32_32x32x16_bf16 v[48:63], v[100:103], v[132:135], v[48:63]
	ds_read_b128 v[100:103], v141 offset:28672
	v_add_u32_e32 v141, v182, v231
	v_cvt_pk_bf16_f32 v182, v116, v117
	v_mfma_f32_32x32x16_bf16 v[16:31], v[150:153], v[136:139], v[16:31]
	v_exp_f32_e32 v138, v142
	v_exp_f32_e32 v139, v143
	v_exp_f32_e32 v142, v144
	v_exp_f32_e32 v143, v145
	v_exp_f32_e32 v144, v180
	v_exp_f32_e32 v145, v181
	v_exp_f32_e32 v136, v158
	s_waitcnt lgkmcnt(0)
	v_mfma_f32_32x32x16_bf16 v[32:47], v[96:99], v[132:135], v[32:47]
	ds_read_b128 v[96:99], v141 offset:16384
	v_exp_f32_e32 v137, v159
	v_cvt_pk_bf16_f32 v180, v112, v113
	v_cvt_pk_bf16_f32 v181, v114, v115
	v_add_f32_e32 v152, v136, v112
	v_add_f32_e32 v153, v137, v113
	v_mfma_f32_32x32x16_bf16 v[16:31], v[100:103], v[132:135], v[16:31]
	v_add_f32_e64 v100, v108, v124
	v_add_f32_e64 v101, v109, v125
	v_add_f32_e64 v102, v142, v116
	v_add_f32_e64 v103, v143, v117
	v_exp_f32_e32 v134, v106
	v_exp_f32_e32 v135, v107
	v_exp_f32_e32 v132, v104
	v_exp_f32_e32 v133, v105
	v_add_f32_e32 v106, v138, v114
	v_add_f32_e32 v107, v139, v115
	v_mfma_f32_32x32x16_bf16 v[64:79], v[154:157], v[168:171], v[64:79]
	v_add_f32_e64 v154, v102, v100
	v_add_f32_e64 v155, v103, v101
	ds_read_b128 v[100:103], v141 offset:20480
	v_add_f32_e64 v104, v134, v122
	v_add_f32_e64 v105, v135, v123
	v_add_f32_e32 v150, v132, v120
	v_add_f32_e32 v151, v133, v121
	v_add_f32_e32 v104, v106, v104
	v_add_f32_e32 v105, v107, v105
	v_cvt_pk_bf16_f32 v184, v132, v133
	v_cvt_pk_bf16_f32 v185, v134, v135
	v_mfma_f32_32x32x16_bf16 v[64:79], v[146:149], v[172:175], v[64:79]
	v_add_f32_e64 v146, v110, v126
	v_add_f32_e64 v147, v111, v127
	v_add_f32_e64 v148, v144, v118
	v_add_f32_e64 v149, v145, v119
	s_waitcnt lgkmcnt(0)
	v_mfma_f32_32x32x16_bf16 v[0:15], v[96:99], v[128:131], v[0:15]
	v_add_f32_e64 v98, v148, v146
	v_add_f32_e64 v99, v149, v147
	v_add_f32_e64 v96, v152, v150
	v_add_f32_e64 v97, v153, v151
	v_add_f32_e64 v98, v104, v98
	v_add_f32_e64 v99, v105, v99
	ds_read_b128 v[104:107], v141 offset:24576
	v_add_f32_e32 v96, v96, v154
	v_add_f32_e32 v97, v97, v155
	s_nop 0
	v_add_f32_e32 v96, v96, v97
	v_mfma_f32_32x32x16_bf16 v[48:63], v[100:103], v[128:131], v[48:63]
	ds_read_b128 v[100:103], v141 offset:28672
	v_add_f32_e32 v97, v98, v99
	v_add_f32_e32 v146, v96, v97
	v_cvt_pk_bf16_f32 v96, v136, v137
	v_cvt_pk_bf16_f32 v97, v138, v139
	v_cvt_pk_bf16_f32 v98, v142, v143
	v_cvt_pk_bf16_f32 v99, v144, v145
	v_mfma_f32_32x32x16_bf16 v[80:95], v[176:179], v[168:171], v[80:95]
	v_cvt_pk_bf16_f32 v176, v120, v121
	v_cvt_pk_bf16_f32 v177, v122, v123
	v_cvt_pk_bf16_f32 v178, v124, v125
	v_cvt_pk_bf16_f32 v179, v126, v127
	s_waitcnt lgkmcnt(0)
	v_mfma_f32_32x32x16_bf16 v[32:47], v[104:107], v[128:131], v[32:47]
	v_mfma_f32_32x32x16_bf16 v[16:31], v[100:103], v[128:131], v[16:31]
	v_add_f32_e32 v100, v194, v146
	v_mfma_f32_32x32x16_bf16 v[80:95], v[238:241], v[172:175], v[80:95]
	s_cbranch_vccz .LBB0_872
	v_pk_mul_f32 v[14:15], v[140:141], v[14:15] op_sel_hi:[0,1]
	v_pk_mul_f32 v[12:13], v[140:141], v[12:13] op_sel_hi:[0,1]
	v_pk_mul_f32 v[10:11], v[140:141], v[10:11] op_sel_hi:[0,1]
	v_pk_mul_f32 v[8:9], v[140:141], v[8:9] op_sel_hi:[0,1]
	v_pk_mul_f32 v[6:7], v[140:141], v[6:7] op_sel_hi:[0,1]
	v_pk_mul_f32 v[4:5], v[140:141], v[4:5] op_sel_hi:[0,1]
	v_pk_mul_f32 v[2:3], v[140:141], v[2:3] op_sel_hi:[0,1]
	v_pk_mul_f32 v[0:1], v[140:141], v[0:1] op_sel_hi:[0,1]
	v_pk_mul_f32 v[62:63], v[140:141], v[62:63] op_sel_hi:[0,1]
	v_pk_mul_f32 v[60:61], v[140:141], v[60:61] op_sel_hi:[0,1]
	v_pk_mul_f32 v[58:59], v[140:141], v[58:59] op_sel_hi:[0,1]
	v_pk_mul_f32 v[56:57], v[140:141], v[56:57] op_sel_hi:[0,1]
	v_pk_mul_f32 v[54:55], v[140:141], v[54:55] op_sel_hi:[0,1]
	v_pk_mul_f32 v[52:53], v[140:141], v[52:53] op_sel_hi:[0,1]
	v_pk_mul_f32 v[50:51], v[140:141], v[50:51] op_sel_hi:[0,1]
	v_pk_mul_f32 v[48:49], v[140:141], v[48:49] op_sel_hi:[0,1]
	v_pk_mul_f32 v[46:47], v[140:141], v[46:47] op_sel_hi:[0,1]
	v_pk_mul_f32 v[44:45], v[140:141], v[44:45] op_sel_hi:[0,1]
	v_pk_mul_f32 v[42:43], v[140:141], v[42:43] op_sel_hi:[0,1]
	v_pk_mul_f32 v[40:41], v[140:141], v[40:41] op_sel_hi:[0,1]
	v_pk_mul_f32 v[38:39], v[140:141], v[38:39] op_sel_hi:[0,1]
	v_pk_mul_f32 v[36:37], v[140:141], v[36:37] op_sel_hi:[0,1]
	v_pk_mul_f32 v[34:35], v[140:141], v[34:35] op_sel_hi:[0,1]
	v_pk_mul_f32 v[32:33], v[140:141], v[32:33] op_sel_hi:[0,1]
	v_pk_mul_f32 v[30:31], v[140:141], v[30:31] op_sel_hi:[0,1]
	v_pk_mul_f32 v[28:29], v[140:141], v[28:29] op_sel_hi:[0,1]
	v_pk_mul_f32 v[26:27], v[140:141], v[26:27] op_sel_hi:[0,1]
	v_pk_mul_f32 v[24:25], v[140:141], v[24:25] op_sel_hi:[0,1]
	v_pk_mul_f32 v[22:23], v[140:141], v[22:23] op_sel_hi:[0,1]
	v_pk_mul_f32 v[20:21], v[140:141], v[20:21] op_sel_hi:[0,1]
	v_pk_mul_f32 v[18:19], v[140:141], v[18:19] op_sel_hi:[0,1]
	v_pk_mul_f32 v[16:17], v[140:141], v[16:17] op_sel_hi:[0,1]

.Lneed_B2:
	v_max_f32_e32 v141, v214, v68
	v_sub_f32_e32 v70, v214, v141
	v_exp_f32_e32 v140, v70
	v_mov_b32_e32 v214, v141
	v_mul_f32_e32 v194, v69, v140
	s_branch .Lneed_B2_join
